# attention: key block means loaded and written to LDS only on the first query block of a unit (they do not depend on the query block)
# speedup vs baseline: 1.0014x; 1.0014x over previous
.LBB0_440:
	v_mov_b32_e32 v36, v136
	s_lshl_b32 s0, s82, 8
	v_ashrrev_i32_e32 v2, 6, v36
	v_and_b32_e32 v37, 63, v36
	v_readfirstlane_b32 s85, v2
	v_add_u32_e32 v2, s77, v2
	v_ashrrev_i32_e32 v3, 31, v2
	v_and_b32_e32 v35, 31, v36
	v_lshlrev_b64 v[2:3], 12, v[2:3]
	s_lshl_b32 s83, s85, 5
	v_lshl_add_u64 v[2:3], s[20:21], 0, v[2:3]
	v_lshlrev_b32_e32 v132, 2, v37
	v_or_b32_e32 v134, s83, v35
	s_add_u32 s48, s12, s0
	v_lshl_add_u64 v[2:3], v[2:3], 0, v[132:133]
	s_addc_u32 s49, s13, 0
	v_ashrrev_i32_e32 v135, 31, v134
	s_cmp_lg_u32 s82, 7
	s_cbranch_scc1 .Lat0_skipld
	global_load_dword v4, v[2:3], off
	global_load_dword v5, v[2:3], off offset:2048
.Lat0_skipld:
	v_lshl_add_u64 v[2:3], s[48:49], 0, v[134:135]
	v_bfe_u32 v34, v36, 5, 1
	v_lshlrev_b64 v[2:3], 10, v[2:3]
	v_lshl_add_u64 v[2:3], s[44:45], 0, v[2:3]
	v_lshlrev_b32_e32 v132, 4, v34
	v_lshl_add_u64 v[2:3], v[2:3], 0, v[132:133]
	global_load_dwordx4 v[80:83], v[2:3], off
	global_load_dwordx4 v[84:87], v[2:3], off offset:32
	global_load_dwordx4 v[88:91], v[2:3], off offset:64
	global_load_dwordx4 v[92:95], v[2:3], off offset:96
	v_ashrrev_i32_e32 v170, 3, v36
	v_and_b32_e32 v171, 7, v36
	v_lshlrev_b32_e32 v172, 3, v171
	v_add_lshl_u32 v173, v170, s12, 9
	v_or3_b32 v172, v173, v172, s78
	s_lshl_b32 s98, s85, 4
	v_lshlrev_b32_e32 v172, 1, v172
	v_or_b32_e32 v173, s12, v37
	s_add_i32 s98, s98, s79
	v_lshl_add_u32 v173, v173, 10, s98
	s_lshl_b32 s99, s82, 18
	v_add_u32_e32 v174, s99, v173
	v_add_u32_e32 v175, s99, v172
	global_load_dwordx4 v[162:165], v175, s[4:5]
	global_load_dwordx4 v[166:169], v174, s[8:9]
	v_lshl_add_u32 v2, v36, 2, 0
	s_mov_b64 s[0:1], -1
	s_cmp_lg_u32 s82, 7
	s_cbranch_scc1 .Lat0_skipw
	s_waitcnt vmcnt(6)
	v_add_f32_e32 v3, v4, v5
	ds_write_b32 v2, v3 offset:36864
.Lat0_skipw:
	s_cmp_lt_u32 s82, 4
	s_waitcnt lgkmcnt(0)
	s_barrier
	s_cbranch_scc1 .LBB0_451
	v_cmp_lt_i32_e32 vcc, v138, v139
	v_and_b32_e32 v40, 32, v36
	v_mov_b32_e32 v39, 0
	v_cndmask_b32_e32 v2, v137, v138, vcc
	v_lshlrev_b32_e32 v38, 2, v2
	s_waitcnt vmcnt(4)
	v_lshlrev_b32_e32 v3, 16, v84
	v_lshlrev_b32_e32 v2, 16, v80
	v_and_b32_e32 v5, 0xffff0000, v84
	v_and_b32_e32 v4, 0xffff0000, v80
	v_lshlrev_b32_e32 v7, 16, v85
	v_lshlrev_b32_e32 v6, 16, v81
	v_and_b32_e32 v9, 0xffff0000, v85
	v_and_b32_e32 v8, 0xffff0000, v81
	v_lshlrev_b32_e32 v11, 16, v86
	v_lshlrev_b32_e32 v10, 16, v82
	v_and_b32_e32 v13, 0xffff0000, v86
	v_and_b32_e32 v12, 0xffff0000, v82
	v_lshlrev_b32_e32 v15, 16, v87
	v_lshlrev_b32_e32 v14, 16, v83
	v_and_b32_e32 v17, 0xffff0000, v87
	v_and_b32_e32 v16, 0xffff0000, v83
	s_waitcnt vmcnt(2)
	v_lshlrev_b32_e32 v19, 16, v92
	v_lshlrev_b32_e32 v18, 16, v88
	v_and_b32_e32 v21, 0xffff0000, v92
	v_and_b32_e32 v20, 0xffff0000, v88
	v_lshlrev_b32_e32 v23, 16, v93
	v_lshlrev_b32_e32 v22, 16, v89
	v_and_b32_e32 v25, 0xffff0000, v93
	v_and_b32_e32 v24, 0xffff0000, v89
	v_lshlrev_b32_e32 v27, 16, v94
	v_lshlrev_b32_e32 v26, 16, v90
	v_and_b32_e32 v29, 0xffff0000, v94
	v_and_b32_e32 v28, 0xffff0000, v90
	v_lshlrev_b32_e32 v31, 16, v95
	v_lshlrev_b32_e32 v30, 16, v91
	v_and_b32_e32 v33, 0xffff0000, v95
	v_and_b32_e32 v32, 0xffff0000, v91
	v_add_u32_e32 v40, s30, v40
	v_mov_b32_e32 v41, 0xff800000
	s_mov_b32 s6, 0
	v_mov_b32_e32 v42, 0xff800000
	v_mov_b32_e32 v45, 0xff800000
	v_mov_b32_e32 v43, 0
	v_mov_b32_e32 v44, 0
